# SB tile loop: mask-free copy of the loop body for kv tiles entirely in the past (the tile-level flag the body already computes), masked body kept for boundary tiles; hazards re-padded (on top of v54)
# speedup vs baseline: 1.0001x; 1.0001x over previous
; #define LAS __attribute__((address_space(3)))
; DI float fast_exp2(float x) { return __builtin_amdgcn_exp2f(x); }
; DI float fast_rcp(float x) { return __builtin_amdgcn_rcpf(x); }
; #define MFMA32(a, b, c) __builtin_amdgcn_mfma_f32_32x32x16_bf16((a), (b), (c), 0, 0, 0)
; DI void qk_tile(f32x16& p0, f32x16& p1, LAS const unsigned char* Ks, const bf16x8 (&qf)[4], int r, int h) {
; #pragma unroll
;     for (int s = 0; s < 4; ++s) {
;         const bf16x8 k0 = *(LAS const bf16x8*)(Ks + (2 * s + h) * 1024 + r * 16);
;         const bf16x8 k1 = *(LAS const bf16x8*)(Ks + (2 * s + h) * 1024 + 512 + r * 16);
;         p0 = MFMA32(k0, qf[s], p0); p1 = MFMA32(k1, qf[s], p1);
;     }
; DI void sb_wg_unit(bf16_t* act, int b, int hh, int Qb, LAS unsigned char* lds, volatile LAS unsigned* ctl, int tid, int wid, int lane) {
;     ...
;             qk_tile(p0, p1, Ks, qf, r, h);
;             const bool diag = (kv0 + 63 >= q0);
;             f32x16 F0, F1;
; #pragma unroll
;             for (int i = 0; i < 16; ++i) {
;                 const int kl = (i & 3) + 8 * (i >> 2) + 4 * h;
;                 { const float e = fast_exp2(fminf(p0[i], 60.f)); const float f = fast_rcp(1.f + e);
;                   const bool valid = !diag || (kv0 + kl < qpos); F0[i] = valid ? f : 1.f; p0[i] = valid ? e * f : 0.f; }
;                 { const float e = fast_exp2(fminf(p1[i], 60.f)); const float f = fast_rcp(1.f + e);
;                   const bool valid = !diag || (kv0 + 32 + kl < qpos); F1[i] = valid ? f : 1.f; p1[i] = valid ? e * f : 0.f; }
;             }
.LBB0_355:
	s_cmp_lt_i32 s12, s21
	s_cbranch_scc1 .Lsb_nd
	v_add_u32_e32 v90, s13, v97
	ds_read_b128 v[34:37], v90
	ds_read_b128 v[38:41], v90 offset:512
	ds_read_b128 v[100:103], v90 offset:2048
	ds_read_b128 v[108:111], v90 offset:2560
	s_cmp_lt_i32 s12, s21
	s_cselect_b64 s[8:9], -1, 0
	s_waitcnt vmcnt(8) lgkmcnt(3)
	v_mfma_f32_32x32x16_bf16 v[50:65], v[34:37], v[66:69], 0
	s_mov_b32 s10, s24
	v_add_u32_e32 v97, 0x4000, v97
	s_waitcnt lgkmcnt(2)
	v_mfma_f32_32x32x16_bf16 v[34:49], v[38:41], v[66:69], 0
	s_waitcnt lgkmcnt(1)
	v_mfma_f32_32x32x16_bf16 v[50:65], v[100:103], v[70:73], v[50:65]
	s_waitcnt lgkmcnt(0)
	v_mfma_f32_32x32x16_bf16 v[34:49], v[108:111], v[70:73], v[34:49]
	ds_read_b128 v[100:103], v90 offset:4096
	ds_read_b128 v[108:111], v90 offset:4608
	s_waitcnt lgkmcnt(1)
	v_mfma_f32_32x32x16_bf16 v[50:65], v[100:103], v[74:77], v[50:65]
	s_waitcnt lgkmcnt(0)
	v_mfma_f32_32x32x16_bf16 v[34:49], v[108:111], v[74:77], v[34:49]
	ds_read_b128 v[100:103], v90 offset:6144
	ds_read_b128 v[108:111], v90 offset:6656
	v_add_u32_e32 v90, s12, v82
	v_subrev_u32_e32 v98, 63, v90
	v_cmp_lt_i32_e32 vcc, v98, v86
	s_or_b64 vcc, s[8:9], vcc
	s_waitcnt lgkmcnt(1)
	v_mfma_f32_32x32x16_bf16 v[50:65], v[100:103], v[78:81], v[50:65]
	v_subrev_u32_e32 v103, 30, v90
	s_waitcnt lgkmcnt(0)
	v_mfma_f32_32x32x16_bf16 v[34:49], v[108:111], v[78:81], v[34:49]
	s_nop 8
	v_min_f32_e32 v50, 0x42700000, v50
	v_exp_f32_e32 v100, v50
	s_nop 0
	v_add_f32_e32 v50, 1.0, v100
	v_min_f32_e32 v34, 0x42700000, v34
	v_rcp_f32_e32 v101, v50
	v_exp_f32_e32 v34, v34
	v_min_f32_e32 v35, 0x42700000, v35
	v_mul_f32_e32 v98, v100, v101
	v_add_f32_e32 v100, 1.0, v34
	v_rcp_f32_e32 v100, v100
	v_cndmask_b32_e32 v50, 1.0, v101, vcc
	v_subrev_u32_e32 v101, 31, v90
	v_cndmask_b32_e32 v98, 0, v98, vcc
	v_cmp_lt_i32_e32 vcc, v101, v86
	s_or_b64 vcc, s[8:9], vcc
	v_mul_f32_e32 v34, v34, v100
	v_cndmask_b32_e32 v101, 1.0, v100, vcc
	v_cndmask_b32_e32 v100, 0, v34, vcc
	v_min_f32_e32 v34, 0x42700000, v51
	v_exp_f32_e32 v51, v34
	v_exp_f32_e32 v35, v35
	v_add_f32_e32 v34, 1.0, v51
	v_rcp_f32_e32 v102, v34
	v_subrev_u32_e32 v34, 62, v90
	v_cmp_lt_i32_e32 vcc, v34, v86
	s_or_b64 vcc, s[8:9], vcc
	v_mul_f32_e32 v51, v51, v102
	v_cndmask_b32_e32 v34, 1.0, v102, vcc
	v_cndmask_b32_e32 v102, 0, v51, vcc
	v_add_f32_e32 v51, 1.0, v35
	v_rcp_f32_e32 v51, v51
	v_cmp_lt_i32_e32 vcc, v103, v86
	s_or_b64 vcc, s[8:9], vcc
	v_mul_f32_e32 v35, v35, v51
	v_cndmask_b32_e32 v104, 0, v35, vcc
	v_min_f32_e32 v35, 0x42700000, v52
	v_exp_f32_e32 v35, v35
	v_cndmask_b32_e32 v103, 1.0, v51, vcc
	v_subrev_u32_e32 v52, 61, v90
	v_cmp_lt_i32_e32 vcc, v52, v86
	v_add_f32_e32 v51, 1.0, v35
	v_rcp_f32_e32 v51, v51
	s_or_b64 vcc, s[8:9], vcc
	v_mul_f32_e32 v35, v35, v51
	v_cndmask_b32_e32 v105, 0, v35, vcc
	v_min_f32_e32 v35, 0x42700000, v36
	v_exp_f32_e32 v35, v35
	v_cndmask_b32_e32 v52, 1.0, v51, vcc
	v_subrev_u32_e32 v51, 29, v90
	v_cmp_lt_i32_e32 vcc, v51, v86
	v_add_f32_e32 v36, 1.0, v35
	v_rcp_f32_e32 v36, v36
	s_or_b64 vcc, s[8:9], vcc
	v_mul_f32_e32 v35, v35, v36
	v_cndmask_b32_e32 v108, 0, v35, vcc
	v_min_f32_e32 v35, 0x42700000, v53
	v_exp_f32_e32 v35, v35
	v_cndmask_b32_e32 v107, 1.0, v36, vcc
	v_add_f32_e32 v36, 1.0, v35
	v_rcp_f32_e32 v51, v36
	v_subrev_u32_e32 v36, 60, v90
	v_cmp_lt_i32_e32 vcc, v36, v86
	s_or_b64 vcc, s[8:9], vcc
	v_mul_f32_e32 v35, v35, v51
	v_cndmask_b32_e32 v109, 0, v35, vcc
	v_min_f32_e32 v35, 0x42700000, v37
	v_exp_f32_e32 v35, v35
	v_cndmask_b32_e32 v36, 1.0, v51, vcc
	v_subrev_u32_e32 v51, 28, v90
	v_cmp_lt_i32_e32 vcc, v51, v86
	v_add_f32_e32 v37, 1.0, v35
	v_rcp_f32_e32 v37, v37
	s_or_b64 vcc, s[8:9], vcc
	v_subrev_u32_e32 v51, 55, v90
	v_mul_f32_e32 v35, v35, v37
	v_cndmask_b32_e32 v111, 0, v35, vcc
	v_min_f32_e32 v35, 0x42700000, v54
	v_exp_f32_e32 v35, v35
	v_cndmask_b32_e32 v110, 1.0, v37, vcc
	v_cmp_lt_i32_e32 vcc, v51, v86
	s_or_b64 vcc, s[8:9], vcc
	v_add_f32_e32 v37, 1.0, v35
	v_rcp_f32_e32 v37, v37
	s_nop 0
	v_mul_f32_e32 v35, v35, v37
	v_cndmask_b32_e32 v54, 0, v35, vcc
	v_min_f32_e32 v35, 0x42700000, v38
	v_exp_f32_e32 v35, v35
	v_cndmask_b32_e32 v51, 1.0, v37, vcc
	v_subrev_u32_e32 v38, 23, v90
	v_cmp_lt_i32_e32 vcc, v38, v86
	v_add_f32_e32 v37, 1.0, v35
	v_rcp_f32_e32 v37, v37
	s_or_b64 vcc, s[8:9], vcc
	v_subrev_u32_e32 v38, 54, v90
	v_mul_f32_e32 v35, v35, v37
	v_cndmask_b32_e32 v112, 0, v35, vcc
	v_min_f32_e32 v35, 0x42700000, v55
	v_exp_f32_e32 v35, v35
	v_cndmask_b32_e32 v53, 1.0, v37, vcc
	v_cmp_lt_i32_e32 vcc, v38, v86
	s_or_b64 vcc, s[8:9], vcc
	v_add_f32_e32 v37, 1.0, v35
	v_rcp_f32_e32 v37, v37
	v_subrev_u32_e32 v38, 22, v90
	v_mul_f32_e32 v35, v35, v37
	v_cndmask_b32_e32 v113, 0, v35, vcc
	v_min_f32_e32 v35, 0x42700000, v39
	v_exp_f32_e32 v35, v35
	v_cndmask_b32_e32 v55, 1.0, v37, vcc
	v_cmp_lt_i32_e32 vcc, v38, v86
	s_or_b64 vcc, s[8:9], vcc
	v_add_f32_e32 v37, 1.0, v35
	v_rcp_f32_e32 v37, v37
	v_subrev_u32_e32 v38, 53, v90
	v_mul_f32_e32 v35, v35, v37
	v_cndmask_b32_e32 v115, 0, v35, vcc
	v_min_f32_e32 v35, 0x42700000, v56
	v_exp_f32_e32 v35, v35
	v_cndmask_b32_e32 v114, 1.0, v37, vcc
	v_cmp_lt_i32_e32 vcc, v38, v86
	s_or_b64 vcc, s[8:9], vcc
	v_add_f32_e32 v37, 1.0, v35
	v_rcp_f32_e32 v37, v37
	v_subrev_u32_e32 v38, 21, v90
	v_mul_f32_e32 v35, v35, v37
	v_cndmask_b32_e32 v117, 0, v35, vcc
	v_min_f32_e32 v35, 0x42700000, v40
	v_exp_f32_e32 v35, v35
	v_cndmask_b32_e32 v116, 1.0, v37, vcc
	v_cmp_lt_i32_e32 vcc, v38, v86
	s_or_b64 vcc, s[8:9], vcc
	v_add_f32_e32 v37, 1.0, v35
	v_rcp_f32_e32 v37, v37
	v_subrev_u32_e32 v38, 52, v90
	v_mul_f32_e32 v35, v35, v37
	v_cndmask_b32_e32 v119, 0, v35, vcc
	v_min_f32_e32 v35, 0x42700000, v57
	v_exp_f32_e32 v35, v35
; DI float fast_exp2(float x) { return __builtin_amdgcn_exp2f(x); }
; DI float fast_rcp(float x) { return __builtin_amdgcn_rcpf(x); }
; DI void sb_wg_unit(bf16_t* act, int b, int hh, int Qb, LAS unsigned char* lds, volatile LAS unsigned* ctl, int tid, int wid, int lane) {
;     ...
;             for (int i = 0; i < 16; ++i) {
;                 const int kl = (i & 3) + 8 * (i >> 2) + 4 * h;
;                 { const float e = fast_exp2(fminf(p0[i], 60.f)); const float f = fast_rcp(1.f + e);
;                   const bool valid = !diag || (kv0 + kl < qpos); F0[i] = valid ? f : 1.f; p0[i] = valid ? e * f : 0.f; }
;                 { const float e = fast_exp2(fminf(p1[i], 60.f)); const float f = fast_rcp(1.f + e);
;                   const bool valid = !diag || (kv0 + 32 + kl < qpos); F1[i] = valid ? f : 1.f; p1[i] = valid ? e * f : 0.f; }
;             }
;             float G[8], Go[8];
; #pragma unroll
;             for (int g = 0; g < 4; ++g) { G[g] = (F0[4 * g] * F0[4 * g + 1]) * (F0[4 * g + 2] * F0[4 * g + 3]); G[4 + g] = (F1[4 * g] * F1[4 * g + 1]) * (F1[4 * g + 2] * F1[4 * g + 3]); }
	v_cndmask_b32_e32 v118, 1.0, v37, vcc
	v_cmp_lt_i32_e32 vcc, v38, v86
	s_or_b64 vcc, s[8:9], vcc
	v_add_f32_e32 v37, 1.0, v35
	v_rcp_f32_e32 v37, v37
	v_subrev_u32_e32 v38, 20, v90
	v_mul_f32_e32 v35, v35, v37
	v_cndmask_b32_e32 v121, 0, v35, vcc
	v_min_f32_e32 v35, 0x42700000, v41
	v_exp_f32_e32 v35, v35
	v_cndmask_b32_e32 v120, 1.0, v37, vcc
	v_cmp_lt_i32_e32 vcc, v38, v86
	s_or_b64 vcc, s[8:9], vcc
	v_add_f32_e32 v37, 1.0, v35
	v_rcp_f32_e32 v37, v37
	v_subrev_u32_e32 v38, 47, v90
	v_subrev_u32_e32 v41, 45, v90
	v_mul_f32_e32 v35, v35, v37
	v_cndmask_b32_e32 v123, 0, v35, vcc
	v_min_f32_e32 v35, 0x42700000, v58
	v_exp_f32_e32 v35, v35
	v_cndmask_b32_e32 v122, 1.0, v37, vcc
	v_cmp_lt_i32_e32 vcc, v38, v86
	s_or_b64 vcc, s[8:9], vcc
	v_add_f32_e32 v37, 1.0, v35
	v_rcp_f32_e32 v37, v37
	v_add_u32_e32 v38, -15, v90
	v_mul_f32_e32 v35, v35, v37
	v_cndmask_b32_e32 v124, 0, v35, vcc
	v_min_f32_e32 v35, 0x42700000, v42
	v_exp_f32_e32 v35, v35
	v_cndmask_b32_e32 v39, 1.0, v37, vcc
	v_cmp_lt_i32_e32 vcc, v38, v86
	s_or_b64 vcc, s[8:9], vcc
	v_add_f32_e32 v37, 1.0, v35
	v_rcp_f32_e32 v37, v37
	v_subrev_u32_e32 v38, 46, v90
	v_mul_f32_e32 v35, v35, v37
	v_cndmask_b32_e32 v125, 0, v35, vcc
	v_min_f32_e32 v35, 0x42700000, v59
	v_exp_f32_e32 v35, v35
	v_cndmask_b32_e32 v40, 1.0, v37, vcc
	v_cmp_lt_i32_e32 vcc, v38, v86
	s_or_b64 vcc, s[8:9], vcc
	v_add_f32_e32 v37, 1.0, v35
	v_rcp_f32_e32 v37, v37
	v_add_u32_e32 v38, -14, v90
	v_mul_f32_e32 v35, v35, v37
	v_cndmask_b32_e32 v127, 0, v35, vcc
	v_min_f32_e32 v35, 0x42700000, v43
	v_exp_f32_e32 v35, v35
	v_cndmask_b32_e32 v126, 1.0, v37, vcc
	v_cmp_lt_i32_e32 vcc, v38, v86
	s_or_b64 vcc, s[8:9], vcc
	v_add_f32_e32 v37, 1.0, v35
	v_rcp_f32_e32 v37, v37
	v_subrev_u32_e32 v43, 38, v90
	v_mul_f32_e32 v35, v35, v37
	v_cndmask_b32_e32 v128, 0, v35, vcc
	v_min_f32_e32 v35, 0x42700000, v60
	v_exp_f32_e32 v35, v35
	v_cndmask_b32_e32 v38, 1.0, v37, vcc
	v_cmp_lt_i32_e32 vcc, v41, v86
	s_or_b64 vcc, s[8:9], vcc
	v_add_f32_e32 v37, 1.0, v35
	v_rcp_f32_e32 v37, v37
	v_add_u32_e32 v41, -13, v90
	v_mul_f32_e32 v35, v35, v37
	v_cndmask_b32_e32 v130, 0, v35, vcc
	v_min_f32_e32 v35, 0x42700000, v44
	v_exp_f32_e32 v35, v35
	v_cndmask_b32_e32 v129, 1.0, v37, vcc
	v_cmp_lt_i32_e32 vcc, v41, v86
	s_or_b64 vcc, s[8:9], vcc
	v_add_f32_e32 v37, 1.0, v35
	v_rcp_f32_e32 v37, v37
	v_subrev_u32_e32 v41, 44, v90
	v_mul_f32_e32 v35, v35, v37
	v_cndmask_b32_e32 v132, 0, v35, vcc
	v_min_f32_e32 v35, 0x42700000, v61
	v_exp_f32_e32 v35, v35
	v_cndmask_b32_e32 v131, 1.0, v37, vcc
	v_cmp_lt_i32_e32 vcc, v41, v86
	s_or_b64 vcc, s[8:9], vcc
	v_add_f32_e32 v37, 1.0, v35
	v_rcp_f32_e32 v37, v37
	v_add_u32_e32 v41, -12, v90
	v_mul_f32_e32 v35, v35, v37
	v_cndmask_b32_e32 v134, 0, v35, vcc
	v_min_f32_e32 v35, 0x42700000, v45
	v_exp_f32_e32 v35, v35
	v_cndmask_b32_e32 v133, 1.0, v37, vcc
	v_cmp_lt_i32_e32 vcc, v41, v86
	s_or_b64 vcc, s[8:9], vcc
	v_add_f32_e32 v37, 1.0, v35
	v_rcp_f32_e32 v37, v37
	v_subrev_u32_e32 v41, 39, v90
	v_mul_f32_e32 v35, v35, v37
	v_cndmask_b32_e32 v136, 0, v35, vcc
	v_min_f32_e32 v35, 0x42700000, v62
	v_exp_f32_e32 v35, v35
	v_cndmask_b32_e32 v135, 1.0, v37, vcc
	v_cmp_lt_i32_e32 vcc, v41, v86
	s_or_b64 vcc, s[8:9], vcc
	v_add_f32_e32 v37, 1.0, v35
	v_rcp_f32_e32 v37, v37
	v_add_u32_e32 v41, -7, v90
	v_mul_f32_e32 v44, v131, v135
	v_mul_f32_e32 v35, v35, v37
	v_cndmask_b32_e32 v137, 0, v35, vcc
	v_min_f32_e32 v35, 0x42700000, v46
	v_exp_f32_e32 v35, v35
	v_cndmask_b32_e32 v42, 1.0, v37, vcc
	v_cmp_lt_i32_e32 vcc, v41, v86
	s_or_b64 vcc, s[8:9], vcc
	v_add_f32_e32 v37, 1.0, v35
	v_rcp_f32_e32 v37, v37
	s_nop 0
	v_mul_f32_e32 v35, v35, v37
	v_cndmask_b32_e32 v138, 0, v35, vcc
	v_min_f32_e32 v35, 0x42700000, v63
	v_exp_f32_e32 v35, v35
	v_cndmask_b32_e32 v41, 1.0, v37, vcc
	v_cmp_lt_i32_e32 vcc, v43, v86
	s_or_b64 vcc, s[8:9], vcc
	v_add_f32_e32 v37, 1.0, v35
	v_rcp_f32_e32 v37, v37
	v_add_u32_e32 v43, -6, v90
	v_mul_f32_e32 v35, v35, v37
	v_cndmask_b32_e32 v139, 0, v35, vcc
	v_min_f32_e32 v35, 0x42700000, v47
	v_exp_f32_e32 v35, v35
	v_cndmask_b32_e32 v56, 1.0, v37, vcc
	v_cmp_lt_i32_e32 vcc, v43, v86
	s_or_b64 vcc, s[8:9], vcc
	v_add_f32_e32 v37, 1.0, v35
	v_rcp_f32_e32 v37, v37
	v_subrev_u32_e32 v43, 37, v90
	v_mul_f32_e32 v35, v35, v37
	v_cndmask_b32_e32 v141, 0, v35, vcc
	v_min_f32_e32 v35, 0x42700000, v64
	v_exp_f32_e32 v35, v35
	v_cndmask_b32_e32 v140, 1.0, v37, vcc
	v_cmp_lt_i32_e32 vcc, v43, v86
	s_or_b64 vcc, s[8:9], vcc
	v_add_f32_e32 v37, 1.0, v35
	v_rcp_f32_e32 v37, v37
	v_add_u32_e32 v43, -5, v90
	v_mul_f32_e32 v41, v41, v140
	v_mul_f32_e32 v35, v35, v37
	v_cndmask_b32_e32 v63, 0, v35, vcc
	v_min_f32_e32 v35, 0x42700000, v48
	v_exp_f32_e32 v35, v35
	v_cndmask_b32_e32 v58, 1.0, v37, vcc
	v_cmp_lt_i32_e32 vcc, v43, v86
	s_or_b64 vcc, s[8:9], vcc
	v_add_f32_e32 v37, 1.0, v35
	v_rcp_f32_e32 v37, v37
	v_subrev_u32_e32 v43, 36, v90
	v_mul_f32_e32 v35, v35, v37
	v_cndmask_b32_e32 v143, 0, v35, vcc
	v_min_f32_e32 v35, 0x42700000, v65
	v_exp_f32_e32 v35, v35
	v_cndmask_b32_e32 v142, 1.0, v37, vcc
	v_cmp_lt_i32_e32 vcc, v43, v86
	s_or_b64 vcc, s[8:9], vcc
	v_add_f32_e32 v37, 1.0, v35
	v_rcp_f32_e32 v37, v37
	v_add_u32_e32 v43, -4, v90
	v_mul_f32_e32 v35, v35, v37
	v_cndmask_b32_e32 v62, 0, v35, vcc
	v_min_f32_e32 v35, 0x42700000, v49
	v_exp_f32_e32 v35, v35
	v_cndmask_b32_e32 v60, 1.0, v37, vcc
	v_cmp_lt_i32_e32 vcc, v43, v86
	s_or_b64 vcc, s[8:9], vcc
	v_add_f32_e32 v37, 1.0, v35
	v_rcp_f32_e32 v37, v37
	s_mov_b32 s8, 0x800000
	v_mul_f32_e32 v35, v35, v37
	v_cndmask_b32_e32 v144, 1.0, v37, vcc
	v_cndmask_b32_e32 v145, 0, v35, vcc
	v_mul_f32_e32 v35, v101, v103
	v_mul_f32_e32 v37, v107, v110
	v_mul_f32_e32 v43, v35, v37
; #define LAS __attribute__((address_space(3)))
; #define MFMA32(a, b, c) __builtin_amdgcn_mfma_f32_32x32x16_bf16((a), (b), (c), 0, 0, 0)
; DI s16x4 vtr(LAS const unsigned char* p) { return __builtin_bit_cast(s16x4, __builtin_amdgcn_ds_read_tr16_b64_v4i16((LAS v4i16_t*)p)); }
; DI void pv_tile(f32x16& o0, f32x16& o1, LAS const unsigned char* Vs, const f32x16& p0, const f32x16& p1, int lane) {
;     const int h = lane >> 5;
;     LAS const unsigned char* vb = Vs + (4 * h + ((lane & 15) >> 2)) * 64 + ((lane >> 4) & 1) * 32 + (lane & 3) * 8;
; #pragma unroll
;     for (int kh = 0; kh < 2; ++kh)
; #pragma unroll
;         for (int s2 = 0; s2 < 2; ++s2) {
;             const bf16x8 pb = kh ? pack8(p1, s2) : pack8(p0, s2);
;             const int ro = (32 * kh + 16 * s2) * 64;
;             const s16x4 l0 = vtr(vb + ro), h0 = vtr(vb + ro + 512), l1 = vtr(vb + 4096 + ro), h1 = vtr(vb + 4096 + ro + 512);
;             const bf16x8 v0 = (bf16x8){l0[0], l0[1], l0[2], l0[3], h0[0], h0[1], h0[2], h0[3]};
;             const bf16x8 v1 = (bf16x8){l1[0], l1[1], l1[2], l1[3], h1[0], h1[1], h1[2], h1[3]};
;             o0 = MFMA32(v0, pb, o0); o1 = MFMA32(v1, pb, o1);
;         }
; DI void sb_wg_unit(bf16_t* act, int b, int hh, int Qb, LAS unsigned char* lds, volatile LAS unsigned* ctl, int tid, int wid, int lane) {
;     ...
;             for (int g = 0; g < 4; ++g) { G[g] = (F0[4 * g] * F0[4 * g + 1]) * (F0[4 * g + 2] * F0[4 * g + 3]); G[4 + g] = (F1[4 * g] * F1[4 * g + 1]) * (F1[4 * g + 2] * F1[4 * g + 3]); }
; #pragma unroll
;             for (int g = 0; g < 8; ++g) Go[g] = xhalf_other(G[g]);
;             float run = C; float A[8];
; #pragma unroll
;             for (int g = 7; g >= 0; --g) { A[g] = run * (h == 0 ? Go[g] : 1.f); run *= (G[g] * Go[g]); }
; #pragma unroll
;             for (int g = 0; g < 4; ++g) {
;                 { float bt = A[g]; p0[4 * g + 3] *= bt; bt *= F0[4 * g + 3]; p0[4 * g + 2] *= bt; bt *= F0[4 * g + 2]; p0[4 * g + 1] *= bt; bt *= F0[4 * g + 1]; p0[4 * g] *= bt; }
;                 { float bt = A[4 + g]; p1[4 * g + 3] *= bt; bt *= F1[4 * g + 3]; p1[4 * g + 2] *= bt; bt *= F1[4 * g + 2]; p1[4 * g + 1] *= bt; bt *= F1[4 * g + 1]; p1[4 * g] *= bt; }
;             }
;             C = run;
;             pv_tile(o0, o1, Vs, p0, p1, lane);
;             if (__all(C < 1.17549435e-38f)) done = true;
;             --t;
	v_mul_f32_e32 v35, v51, v55
	v_mul_f32_e32 v37, v116, v120
	v_mul_f32_e32 v51, v35, v37
	v_mul_f32_e32 v35, v53, v114
	v_mul_f32_e32 v37, v118, v122
	v_mul_f32_e32 v37, v35, v37
	v_mul_f32_e32 v35, v39, v126
	v_mul_f32_e32 v39, v129, v133
	v_mul_f32_e32 v46, v35, v39
	v_mov_b32_e32 v35, v51
	v_mov_b32_e32 v45, v51
	s_nop 1
	v_permlane32_swap_b32_e32 v35, v45
	v_xor_b32_e32 v35, v35, v45
	v_mov_b32_e32 v45, v46
	v_mov_b32_e32 v47, v46
	s_nop 1
	v_permlane32_swap_b32_e32 v45, v47
	v_xor_b32_e32 v45, v45, v47
	v_xor_b32_e32 v47, v45, v46
	v_mov_b32_e32 v45, v43
	v_mov_b32_e32 v48, v43
	s_nop 1
	v_permlane32_swap_b32_e32 v45, v48
	v_xor_b32_e32 v45, v45, v48
	v_xor_b32_e32 v57, v45, v43
	v_mov_b32_e32 v45, v37
	v_mov_b32_e32 v48, v37
	v_mul_f32_e32 v39, v142, v144
	s_nop 0
	v_permlane32_swap_b32_e32 v45, v48
	v_xor_b32_e32 v45, v45, v48
	v_pk_mul_f32 v[40:41], v[40:41], v[38:39]
	v_xor_b32_e32 v48, v45, v37
	v_mov_b32_e32 v39, v41
	v_mov_b32_e32 v45, v41
	s_nop 1
	v_permlane32_swap_b32_e32 v39, v45
	v_xor_b32_e32 v39, v39, v45
	v_xor_b32_e32 v45, v39, v41
	v_pk_mul_f32 v[40:41], v[40:41], v[44:45]
	v_mul_f32_e32 v59, v37, v48
	v_mov_b32_e32 v39, v40
	v_mov_b32_e32 v44, v40
	s_nop 1
	v_permlane32_swap_b32_e32 v39, v44
	v_xor_b32_e32 v39, v39, v44
	v_xor_b32_e32 v90, v39, v40
	v_cndmask_b32_e64 v39, 1.0, v45, s[42:43]
	v_mul_f32_e32 v101, v91, v39
	v_cndmask_b32_e64 v39, 1.0, v90, s[42:43]
	v_pk_mul_f32 v[40:41], v[40:41], v[90:91]
	v_pk_mul_f32 v[42:43], v[42:43], v[56:57]
	v_mul_f32_e32 v49, v39, v41
	v_pk_mul_f32 v[40:41], v[40:41], v[40:41] op_sel:[0,1] op_sel_hi:[1,0]
	v_cndmask_b32_e64 v39, 1.0, v48, s[42:43]
	v_mov_b32_e32 v61, v40
	v_mul_f32_e32 v45, v39, v40
	v_pk_mul_f32 v[40:41], v[58:59], v[60:61]
	v_cndmask_b32_e64 v37, 1.0, v57, s[42:43]
	v_pk_mul_f32 v[42:43], v[42:43], v[40:41]
	v_mul_f32_e32 v48, v37, v41
	v_mov_b32_e32 v39, v42
	v_mov_b32_e32 v40, v42
	s_nop 1
	v_permlane32_swap_b32_e32 v39, v40
	v_xor_b32_e32 v39, v39, v40
	v_xor_b32_e32 v39, v39, v42
	v_cndmask_b32_e64 v37, 1.0, v39, s[42:43]
	v_mul_f32_e32 v64, v37, v43
	v_mul_f32_e32 v37, v42, v39
	v_xor_b32_e32 v35, v35, v51
	v_mul_f32_e32 v37, v37, v43
	v_mul_f32_e32 v53, v46, v47
	v_pk_mul_f32 v[40:41], v[52:53], v[36:37]
	v_pk_mul_f32 v[42:43], v[50:51], v[34:35]
	v_cndmask_b32_e64 v39, 1.0, v47, s[42:43]
	v_pk_mul_f32 v[42:43], v[42:43], v[40:41]
	v_mul_f32_e32 v57, v39, v37
	v_cndmask_b32_e64 v39, 1.0, v35, s[42:43]
	v_mov_b32_e32 v35, v42
	v_mov_b32_e32 v37, v42
	s_nop 1
	v_permlane32_swap_b32_e32 v35, v37
	v_xor_b32_e32 v35, v35, v37
	v_xor_b32_e32 v35, v35, v42
	v_mul_f32_e32 v39, v39, v41
	v_cndmask_b32_e64 v37, 1.0, v35, s[42:43]
	v_mul_f32_e32 v37, v37, v43
	v_mul_f32_e32 v35, v42, v35
	v_mul_f32_e32 v50, v121, v39
	v_mul_f32_e32 v39, v120, v39
	v_mul_f32_e32 v91, v35, v43
	v_mul_f32_e32 v35, v36, v37
	v_mul_f32_e32 v51, v117, v39
	v_mul_f32_e32 v39, v116, v39
	v_mul_f32_e32 v42, v105, v35
	v_mul_f32_e32 v35, v52, v35
	v_mul_f32_e32 v52, v113, v39
	v_mul_f32_e32 v39, v55, v39
	v_mul_f32_e32 v43, v122, v45
	v_mul_f32_e32 v55, v54, v39
	v_mul_f32_e32 v39, v123, v45
	v_mul_f32_e32 v45, v118, v43
	v_mul_f32_e32 v41, v119, v43
	v_mul_f32_e32 v43, v115, v45
	v_mul_f32_e32 v45, v114, v45
	v_mul_f32_e32 v46, v112, v45
	v_mul_f32_e32 v45, v133, v57
	v_mul_f32_e32 v54, v134, v57
	v_mul_f32_e32 v57, v130, v45
	v_mul_f32_e32 v45, v129, v45
	v_mul_f32_e32 v59, v127, v45
	v_mul_f32_e32 v45, v126, v45
	v_mul_f32_e32 v34, v34, v35
	v_mul_f32_e32 v36, v110, v48
	v_mul_f32_e32 v61, v124, v45
	v_mul_f32_e32 v45, v136, v49
	v_mul_f32_e32 v49, v135, v49
	v_add_u32_e32 v90, s13, v87
	v_mul_f32_e32 v40, v109, v37
	v_mul_f32_e32 v44, v102, v35
	v_mul_f32_e32 v47, v98, v34
	v_mul_f32_e32 v34, v111, v48
	v_mul_f32_e32 v35, v108, v36
	v_mul_f32_e32 v53, v131, v49
	ds_read_b64_tr_b16 v[108:109], v90 offset:8192
	ds_read_b64_tr_b16 v[110:111], v90 offset:8704
	ds_read_b64_tr_b16 v[112:113], v90 offset:12288
	ds_read_b64_tr_b16 v[114:115], v90 offset:12800
	v_mul_f32_e32 v48, v132, v49
	v_mul_f32_e32 v49, v128, v53
	v_mul_f32_e32 v38, v38, v53
	v_mul_f32_e32 v53, v60, v64
	v_mul_f32_e32 v37, v107, v36
	v_mul_f32_e32 v63, v63, v53
	v_mul_f32_e32 v53, v58, v53
	v_mul_f32_e32 v36, v104, v37
	v_mul_f32_e32 v37, v103, v37
	v_mul_f32_e32 v62, v62, v64
	v_mul_f32_e32 v64, v139, v53
	v_mul_f32_e32 v53, v56, v53
	v_mul_f32_e32 v37, v100, v37
	v_mul_f32_e32 v65, v137, v53
	v_mul_f32_e32 v53, v145, v101
	v_mul_f32_e32 v58, v144, v101
	v_cvt_pk_bf16_f32 v100, v47, v44
	v_cvt_pk_bf16_f32 v101, v42, v40
	v_cvt_pk_bf16_f32 v102, v55, v52
	v_cvt_pk_bf16_f32 v103, v51, v50
	v_mul_f32_e32 v38, v125, v38
	v_mul_f32_e32 v60, v142, v58
	s_waitcnt lgkmcnt(2)
	v_mfma_f32_32x32x16_bf16 v[18:33], v[108:111], v[100:103], v[18:33]
	v_mul_f32_e32 v56, v143, v58
	v_mul_f32_e32 v58, v141, v60
	v_mul_f32_e32 v60, v140, v60
	v_mul_f32_e32 v60, v138, v60
	v_cmp_gt_f32_e32 vcc, s8, v91
	s_cmp_eq_u64 vcc, exec
	s_cselect_b64 s[8:9], -1, 0
	s_waitcnt lgkmcnt(0)
	v_mfma_f32_32x32x16_bf16 v[2:17], v[112:115], v[100:103], v[2:17]
	v_cvt_pk_bf16_f32 v102, v65, v64
	v_cvt_pk_bf16_f32 v103, v63, v62
	ds_read_b64_tr_b16 v[62:63], v90 offset:9216
	ds_read_b64_tr_b16 v[64:65], v90 offset:9728
	ds_read_b64_tr_b16 v[108:109], v90 offset:13312
	ds_read_b64_tr_b16 v[110:111], v90 offset:13824
	v_cvt_pk_bf16_f32 v100, v61, v59
	v_cvt_pk_bf16_f32 v101, v57, v54
	s_add_i32 s24, s24, -1
	s_cmp_le_i32 s10, s23
	s_waitcnt lgkmcnt(2)
	v_mfma_f32_32x32x16_bf16 v[18:33], v[62:65], v[100:103], v[18:33]
	v_cvt_pk_bf16_f32 v62, v37, v36
	v_cvt_pk_bf16_f32 v63, v35, v34
	v_cvt_pk_bf16_f32 v64, v46, v43
	v_cvt_pk_bf16_f32 v65, v41, v39
	ds_read_b64_tr_b16 v[34:35], v90 offset:10240
	ds_read_b64_tr_b16 v[36:37], v90 offset:10752
	ds_read_b64_tr_b16 v[40:41], v90 offset:14336
	ds_read_b64_tr_b16 v[42:43], v90 offset:14848
	s_cselect_b64 s[10:11], -1, 0
	s_or_b64 s[10:11], s[8:9], s[10:11]
	s_waitcnt lgkmcnt(4)
	v_mfma_f32_32x32x16_bf16 v[2:17], v[108:111], v[100:103], v[2:17]
	s_sub_i32 s12, s12, 64
	v_add_u32_e32 v87, 0x4000, v87
	s_andn2_b64 vcc, exec, s[10:11]
	s_waitcnt lgkmcnt(2)
	v_mfma_f32_32x32x16_bf16 v[18:33], v[34:37], v[62:65], v[18:33]
	v_cvt_pk_bf16_f32 v34, v38, v49
	v_cvt_pk_bf16_f32 v35, v48, v45
	v_cvt_pk_bf16_f32 v36, v60, v58
	v_cvt_pk_bf16_f32 v37, v56, v53
	s_waitcnt lgkmcnt(0)
	v_mfma_f32_32x32x16_bf16 v[2:17], v[40:43], v[62:65], v[2:17]
	ds_read_b64_tr_b16 v[38:39], v90 offset:11264
	ds_read_b64_tr_b16 v[40:41], v90 offset:11776
	ds_read_b64_tr_b16 v[42:43], v90 offset:15360
	ds_read_b64_tr_b16 v[44:45], v90 offset:15872
	s_waitcnt lgkmcnt(2)
	v_mfma_f32_32x32x16_bf16 v[18:33], v[38:41], v[34:37], v[18:33]
	s_waitcnt lgkmcnt(0)
	v_mfma_f32_32x32x16_bf16 v[2:17], v[42:45], v[34:37], v[2:17]
	s_cbranch_vccnz .LBB0_355
	s_branch .LBB0_356
; #define LAS __attribute__((address_space(3)))
; DI float fast_exp2(float x) { return __builtin_amdgcn_exp2f(x); }
; DI float fast_rcp(float x) { return __builtin_amdgcn_rcpf(x); }
; #define MFMA32(a, b, c) __builtin_amdgcn_mfma_f32_32x32x16_bf16((a), (b), (c), 0, 0, 0)
; DI void qk_tile(f32x16& p0, f32x16& p1, LAS const unsigned char* Ks, const bf16x8 (&qf)[4], int r, int h) {
; #pragma unroll
;     for (int s = 0; s < 4; ++s) {
;         const bf16x8 k0 = *(LAS const bf16x8*)(Ks + (2 * s + h) * 1024 + r * 16);
;         const bf16x8 k1 = *(LAS const bf16x8*)(Ks + (2 * s + h) * 1024 + 512 + r * 16);
;         p0 = MFMA32(k0, qf[s], p0); p1 = MFMA32(k1, qf[s], p1);
;     }
; DI void sb_wg_unit(bf16_t* act, int b, int hh, int Qb, LAS unsigned char* lds, volatile LAS unsigned* ctl, int tid, int wid, int lane) {
;     ...
;             qk_tile(p0, p1, Ks, qf, r, h);
;             const bool diag = (kv0 + 63 >= q0);
;             f32x16 F0, F1;
; #pragma unroll
;             for (int i = 0; i < 16; ++i) {
;                 const int kl = (i & 3) + 8 * (i >> 2) + 4 * h;
;                 { const float e = fast_exp2(fminf(p0[i], 60.f)); const float f = fast_rcp(1.f + e);
;                   const bool valid = !diag || (kv0 + kl < qpos); F0[i] = valid ? f : 1.f; p0[i] = valid ? e * f : 0.f; }
;                 { const float e = fast_exp2(fminf(p1[i], 60.f)); const float f = fast_rcp(1.f + e);
;                   const bool valid = !diag || (kv0 + 32 + kl < qpos); F1[i] = valid ? f : 1.f; p1[i] = valid ? e * f : 0.f; }
;             }
.Lsb_nd:
	v_add_u32_e32 v90, s13, v97
	ds_read_b128 v[34:37], v90
	ds_read_b128 v[38:41], v90 offset:512
	ds_read_b128 v[100:103], v90 offset:2048
	ds_read_b128 v[108:111], v90 offset:2560
	s_cmp_lt_i32 s12, s21
	s_cselect_b64 s[8:9], -1, 0
	s_waitcnt vmcnt(8) lgkmcnt(3)
	v_mfma_f32_32x32x16_bf16 v[50:65], v[34:37], v[66:69], 0
	s_mov_b32 s10, s24
	v_add_u32_e32 v97, 0x4000, v97
	s_waitcnt lgkmcnt(2)
	v_mfma_f32_32x32x16_bf16 v[34:49], v[38:41], v[66:69], 0
	s_waitcnt lgkmcnt(1)
	v_mfma_f32_32x32x16_bf16 v[50:65], v[100:103], v[70:73], v[50:65]
	s_waitcnt lgkmcnt(0)
	v_mfma_f32_32x32x16_bf16 v[34:49], v[108:111], v[70:73], v[34:49]
	ds_read_b128 v[100:103], v90 offset:4096
	ds_read_b128 v[108:111], v90 offset:4608
	s_waitcnt lgkmcnt(1)
	v_mfma_f32_32x32x16_bf16 v[50:65], v[100:103], v[74:77], v[50:65]
	s_waitcnt lgkmcnt(0)
	v_mfma_f32_32x32x16_bf16 v[34:49], v[108:111], v[74:77], v[34:49]
	ds_read_b128 v[100:103], v90 offset:6144
	ds_read_b128 v[108:111], v90 offset:6656
	v_add_u32_e32 v90, s12, v82
	s_waitcnt lgkmcnt(1)
	v_mfma_f32_32x32x16_bf16 v[50:65], v[100:103], v[78:81], v[50:65]
	s_waitcnt lgkmcnt(0)
	v_mfma_f32_32x32x16_bf16 v[34:49], v[108:111], v[78:81], v[34:49]
	s_nop 8
	s_nop 0
	v_min_f32_e32 v50, 0x42700000, v50
	v_exp_f32_e32 v100, v50
	s_nop 0
	v_add_f32_e32 v50, 1.0, v100
	v_min_f32_e32 v34, 0x42700000, v34
	v_rcp_f32_e32 v101, v50
	v_exp_f32_e32 v34, v34
	v_min_f32_e32 v35, 0x42700000, v35
	v_mul_f32_e32 v98, v100, v101
	v_add_f32_e32 v100, 1.0, v34
	v_rcp_f32_e32 v100, v100
	v_mov_b32_e32 v50, v101
	v_mul_f32_e32 v34, v34, v100
	v_mov_b32_e32 v101, v100
	v_mov_b32_e32 v100, v34
	v_min_f32_e32 v34, 0x42700000, v51
	v_exp_f32_e32 v51, v34
	v_exp_f32_e32 v35, v35
	v_add_f32_e32 v34, 1.0, v51
	v_rcp_f32_e32 v102, v34
	s_nop 0
	v_mul_f32_e32 v51, v51, v102
	v_mov_b32_e32 v34, v102
	v_mov_b32_e32 v102, v51
	v_add_f32_e32 v51, 1.0, v35
	v_rcp_f32_e32 v51, v51
	s_nop 0
	v_mul_f32_e32 v35, v35, v51
	v_mov_b32_e32 v104, v35
	v_min_f32_e32 v35, 0x42700000, v52
	v_exp_f32_e32 v35, v35
	v_mov_b32_e32 v103, v51
	v_add_f32_e32 v51, 1.0, v35
	v_rcp_f32_e32 v51, v51
	s_nop 0
	v_mul_f32_e32 v35, v35, v51
	v_mov_b32_e32 v105, v35
	v_min_f32_e32 v35, 0x42700000, v36
	v_exp_f32_e32 v35, v35
	v_mov_b32_e32 v52, v51
	v_add_f32_e32 v36, 1.0, v35
	v_rcp_f32_e32 v36, v36
	s_nop 0
	v_mul_f32_e32 v35, v35, v36
	v_mov_b32_e32 v108, v35
	v_min_f32_e32 v35, 0x42700000, v53
	v_exp_f32_e32 v35, v35
	v_mov_b32_e32 v107, v36
	v_add_f32_e32 v36, 1.0, v35
	v_rcp_f32_e32 v51, v36
	s_nop 0
	v_mul_f32_e32 v35, v35, v51
	v_mov_b32_e32 v109, v35
	v_min_f32_e32 v35, 0x42700000, v37
	v_exp_f32_e32 v35, v35
	v_mov_b32_e32 v36, v51
	v_add_f32_e32 v37, 1.0, v35
	v_rcp_f32_e32 v37, v37
	s_nop 0
	v_mul_f32_e32 v35, v35, v37
	v_mov_b32_e32 v111, v35
	v_min_f32_e32 v35, 0x42700000, v54
	v_exp_f32_e32 v35, v35
	v_mov_b32_e32 v110, v37
	v_add_f32_e32 v37, 1.0, v35
	v_rcp_f32_e32 v37, v37
	s_nop 0
	v_mul_f32_e32 v35, v35, v37
	v_mov_b32_e32 v54, v35
	v_min_f32_e32 v35, 0x42700000, v38
	v_exp_f32_e32 v35, v35
	v_mov_b32_e32 v51, v37
	v_add_f32_e32 v37, 1.0, v35
	v_rcp_f32_e32 v37, v37
	s_nop 0
	v_mul_f32_e32 v35, v35, v37
	v_mov_b32_e32 v112, v35
	v_min_f32_e32 v35, 0x42700000, v55
	v_exp_f32_e32 v35, v35
	v_mov_b32_e32 v53, v37
	v_add_f32_e32 v37, 1.0, v35
	v_rcp_f32_e32 v37, v37
	s_nop 0
	v_mul_f32_e32 v35, v35, v37
	v_mov_b32_e32 v113, v35
	v_min_f32_e32 v35, 0x42700000, v39
	v_exp_f32_e32 v35, v35
	v_mov_b32_e32 v55, v37
	v_add_f32_e32 v37, 1.0, v35
	v_rcp_f32_e32 v37, v37
	s_nop 0
	v_mul_f32_e32 v35, v35, v37
	v_mov_b32_e32 v115, v35
	v_min_f32_e32 v35, 0x42700000, v56
	v_exp_f32_e32 v35, v35
	v_mov_b32_e32 v114, v37
	v_add_f32_e32 v37, 1.0, v35
	v_rcp_f32_e32 v37, v37
	s_nop 0
	v_mul_f32_e32 v35, v35, v37
	v_mov_b32_e32 v117, v35
	v_min_f32_e32 v35, 0x42700000, v40
	v_exp_f32_e32 v35, v35
	v_mov_b32_e32 v116, v37
	v_add_f32_e32 v37, 1.0, v35
	v_rcp_f32_e32 v37, v37
	s_nop 0
	v_mul_f32_e32 v35, v35, v37
	v_mov_b32_e32 v119, v35
	v_min_f32_e32 v35, 0x42700000, v57
	v_exp_f32_e32 v35, v35
	v_mov_b32_e32 v118, v37
	v_add_f32_e32 v37, 1.0, v35
	v_rcp_f32_e32 v37, v37
	s_nop 0
	v_mul_f32_e32 v35, v35, v37
	v_mov_b32_e32 v121, v35
	v_min_f32_e32 v35, 0x42700000, v41
	v_exp_f32_e32 v35, v35
	v_mov_b32_e32 v120, v37
	v_add_f32_e32 v37, 1.0, v35
	v_rcp_f32_e32 v37, v37
	s_nop 0
	v_mul_f32_e32 v35, v35, v37
	v_mov_b32_e32 v123, v35
	v_min_f32_e32 v35, 0x42700000, v58
	v_exp_f32_e32 v35, v35
	v_mov_b32_e32 v122, v37
	v_add_f32_e32 v37, 1.0, v35
	v_rcp_f32_e32 v37, v37
	s_nop 0
	v_mul_f32_e32 v35, v35, v37
	v_mov_b32_e32 v124, v35
	v_min_f32_e32 v35, 0x42700000, v42
	v_exp_f32_e32 v35, v35
	v_mov_b32_e32 v39, v37
	v_add_f32_e32 v37, 1.0, v35
	v_rcp_f32_e32 v37, v37
	s_nop 0
	v_mul_f32_e32 v35, v35, v37
	v_mov_b32_e32 v125, v35
	v_min_f32_e32 v35, 0x42700000, v59
	v_exp_f32_e32 v35, v35
	v_mov_b32_e32 v40, v37
	v_add_f32_e32 v37, 1.0, v35
	v_rcp_f32_e32 v37, v37
	s_nop 0
	v_mul_f32_e32 v35, v35, v37
	v_mov_b32_e32 v127, v35
	v_min_f32_e32 v35, 0x42700000, v43
	v_exp_f32_e32 v35, v35
	v_mov_b32_e32 v126, v37
	v_add_f32_e32 v37, 1.0, v35
	v_rcp_f32_e32 v37, v37
	s_nop 0
	v_mul_f32_e32 v35, v35, v37
	v_mov_b32_e32 v128, v35
	v_min_f32_e32 v35, 0x42700000, v60
	v_exp_f32_e32 v35, v35
	v_mov_b32_e32 v38, v37
	v_add_f32_e32 v37, 1.0, v35
	v_rcp_f32_e32 v37, v37
	s_nop 0
	v_mul_f32_e32 v35, v35, v37
	v_mov_b32_e32 v130, v35
	v_min_f32_e32 v35, 0x42700000, v44
	v_exp_f32_e32 v35, v35
	v_mov_b32_e32 v129, v37
	v_add_f32_e32 v37, 1.0, v35
	v_rcp_f32_e32 v37, v37
	s_nop 0
	v_mul_f32_e32 v35, v35, v37
	v_mov_b32_e32 v132, v35
	v_min_f32_e32 v35, 0x42700000, v61
	v_exp_f32_e32 v35, v35
; DI float fast_exp2(float x) { return __builtin_amdgcn_exp2f(x); }
; DI float fast_rcp(float x) { return __builtin_amdgcn_rcpf(x); }
; DI float xhalf_other(float v) { const unsigned b = __float_as_uint(v); auto rr = __builtin_amdgcn_permlane32_swap(b, b, false, false); return __uint_as_float(rr[0] ^ rr[1] ^ b); }
; DI void sb_wg_unit(bf16_t* act, int b, int hh, int Qb, LAS unsigned char* lds, volatile LAS unsigned* ctl, int tid, int wid, int lane) {
;     ...
;             for (int i = 0; i < 16; ++i) {
;                 const int kl = (i & 3) + 8 * (i >> 2) + 4 * h;
;                 { const float e = fast_exp2(fminf(p0[i], 60.f)); const float f = fast_rcp(1.f + e);
;                   const bool valid = !diag || (kv0 + kl < qpos); F0[i] = valid ? f : 1.f; p0[i] = valid ? e * f : 0.f; }
;                 { const float e = fast_exp2(fminf(p1[i], 60.f)); const float f = fast_rcp(1.f + e);
;                   const bool valid = !diag || (kv0 + 32 + kl < qpos); F1[i] = valid ? f : 1.f; p1[i] = valid ? e * f : 0.f; }
;             }
;             float G[8], Go[8];
; #pragma unroll
;             for (int g = 0; g < 4; ++g) { G[g] = (F0[4 * g] * F0[4 * g + 1]) * (F0[4 * g + 2] * F0[4 * g + 3]); G[4 + g] = (F1[4 * g] * F1[4 * g + 1]) * (F1[4 * g + 2] * F1[4 * g + 3]); }
; #pragma unroll
;             for (int g = 0; g < 8; ++g) Go[g] = xhalf_other(G[g]);
;             float run = C; float A[8];
; #pragma unroll
;             for (int g = 7; g >= 0; --g) { A[g] = run * (h == 0 ? Go[g] : 1.f); run *= (G[g] * Go[g]); }
; #pragma unroll
;             for (int g = 0; g < 4; ++g) {
;                 { float bt = A[g]; p0[4 * g + 3] *= bt; bt *= F0[4 * g + 3]; p0[4 * g + 2] *= bt; bt *= F0[4 * g + 2]; p0[4 * g + 1] *= bt; bt *= F0[4 * g + 1]; p0[4 * g] *= bt; }
;                 { float bt = A[4 + g]; p1[4 * g + 3] *= bt; bt *= F1[4 * g + 3]; p1[4 * g + 2] *= bt; bt *= F1[4 * g + 2]; p1[4 * g + 1] *= bt; bt *= F1[4 * g + 1]; p1[4 * g] *= bt; }
;             }
;             C = run;
	v_mov_b32_e32 v131, v37
	v_add_f32_e32 v37, 1.0, v35
	v_rcp_f32_e32 v37, v37
	s_nop 0
	v_mul_f32_e32 v35, v35, v37
	v_mov_b32_e32 v134, v35
	v_min_f32_e32 v35, 0x42700000, v45
	v_exp_f32_e32 v35, v35
	v_mov_b32_e32 v133, v37
	v_add_f32_e32 v37, 1.0, v35
	v_rcp_f32_e32 v37, v37
	s_nop 0
	v_mul_f32_e32 v35, v35, v37
	v_mov_b32_e32 v136, v35
	v_min_f32_e32 v35, 0x42700000, v62
	v_exp_f32_e32 v35, v35
	v_mov_b32_e32 v135, v37
	v_add_f32_e32 v37, 1.0, v35
	v_rcp_f32_e32 v37, v37
	v_mul_f32_e32 v44, v131, v135
	v_mul_f32_e32 v35, v35, v37
	v_mov_b32_e32 v137, v35
	v_min_f32_e32 v35, 0x42700000, v46
	v_exp_f32_e32 v35, v35
	v_mov_b32_e32 v42, v37
	v_add_f32_e32 v37, 1.0, v35
	v_rcp_f32_e32 v37, v37
	s_nop 0
	v_mul_f32_e32 v35, v35, v37
	v_mov_b32_e32 v138, v35
	v_min_f32_e32 v35, 0x42700000, v63
	v_exp_f32_e32 v35, v35
	v_mov_b32_e32 v41, v37
	v_add_f32_e32 v37, 1.0, v35
	v_rcp_f32_e32 v37, v37
	s_nop 0
	v_mul_f32_e32 v35, v35, v37
	v_mov_b32_e32 v139, v35
	v_min_f32_e32 v35, 0x42700000, v47
	v_exp_f32_e32 v35, v35
	v_mov_b32_e32 v56, v37
	v_add_f32_e32 v37, 1.0, v35
	v_rcp_f32_e32 v37, v37
	s_nop 0
	v_mul_f32_e32 v35, v35, v37
	v_mov_b32_e32 v141, v35
	v_min_f32_e32 v35, 0x42700000, v64
	v_exp_f32_e32 v35, v35
	v_mov_b32_e32 v140, v37
	v_add_f32_e32 v37, 1.0, v35
	v_rcp_f32_e32 v37, v37
	v_mul_f32_e32 v41, v41, v140
	v_mul_f32_e32 v35, v35, v37
	v_mov_b32_e32 v63, v35
	v_min_f32_e32 v35, 0x42700000, v48
	v_exp_f32_e32 v35, v35
	v_mov_b32_e32 v58, v37
	v_add_f32_e32 v37, 1.0, v35
	v_rcp_f32_e32 v37, v37
	s_nop 0
	v_mul_f32_e32 v35, v35, v37
	v_mov_b32_e32 v143, v35
	v_min_f32_e32 v35, 0x42700000, v65
	v_exp_f32_e32 v35, v35
	v_mov_b32_e32 v142, v37
	v_add_f32_e32 v37, 1.0, v35
	v_rcp_f32_e32 v37, v37
	s_nop 0
	v_mul_f32_e32 v35, v35, v37
	v_mov_b32_e32 v62, v35
	v_min_f32_e32 v35, 0x42700000, v49
	v_exp_f32_e32 v35, v35
	v_mov_b32_e32 v60, v37
	v_add_f32_e32 v37, 1.0, v35
	v_rcp_f32_e32 v37, v37
	s_mov_b32 s8, 0x800000
	v_mul_f32_e32 v35, v35, v37
	v_mov_b32_e32 v144, v37
	v_mov_b32_e32 v145, v35
	v_mul_f32_e32 v35, v101, v103
	v_mul_f32_e32 v37, v107, v110
	v_mul_f32_e32 v43, v35, v37
	v_mul_f32_e32 v35, v51, v55
	v_mul_f32_e32 v37, v116, v120
	v_mul_f32_e32 v51, v35, v37
	v_mul_f32_e32 v35, v53, v114
	v_mul_f32_e32 v37, v118, v122
	v_mul_f32_e32 v37, v35, v37
	v_mul_f32_e32 v35, v39, v126
	v_mul_f32_e32 v39, v129, v133
	v_mul_f32_e32 v46, v35, v39
	v_mov_b32_e32 v35, v51
	v_mov_b32_e32 v45, v51
	s_nop 1
	v_permlane32_swap_b32_e32 v35, v45
	v_xor_b32_e32 v35, v35, v45
	v_mov_b32_e32 v45, v46
	v_mov_b32_e32 v47, v46
	s_nop 1
	v_permlane32_swap_b32_e32 v45, v47
	v_xor_b32_e32 v45, v45, v47
	v_xor_b32_e32 v47, v45, v46
	v_mov_b32_e32 v45, v43
	v_mov_b32_e32 v48, v43
	s_nop 1
	v_permlane32_swap_b32_e32 v45, v48
	v_xor_b32_e32 v45, v45, v48
	v_xor_b32_e32 v57, v45, v43
	v_mov_b32_e32 v45, v37
	v_mov_b32_e32 v48, v37
	v_mul_f32_e32 v39, v142, v144
	s_nop 0
	v_permlane32_swap_b32_e32 v45, v48
	v_xor_b32_e32 v45, v45, v48
	v_pk_mul_f32 v[40:41], v[40:41], v[38:39]
	v_xor_b32_e32 v48, v45, v37
	v_mov_b32_e32 v39, v41
	v_mov_b32_e32 v45, v41
	s_nop 1
	v_permlane32_swap_b32_e32 v39, v45
	v_xor_b32_e32 v39, v39, v45
	v_xor_b32_e32 v45, v39, v41
	v_pk_mul_f32 v[40:41], v[40:41], v[44:45]
	v_mul_f32_e32 v59, v37, v48
	v_mov_b32_e32 v39, v40
	v_mov_b32_e32 v44, v40
	s_nop 1
	v_permlane32_swap_b32_e32 v39, v44
	v_xor_b32_e32 v39, v39, v44
	v_xor_b32_e32 v90, v39, v40
	v_cndmask_b32_e64 v39, 1.0, v45, s[42:43]
	v_mul_f32_e32 v101, v91, v39
	v_cndmask_b32_e64 v39, 1.0, v90, s[42:43]
	v_pk_mul_f32 v[40:41], v[40:41], v[90:91]
	v_pk_mul_f32 v[42:43], v[42:43], v[56:57]
	v_mul_f32_e32 v49, v39, v41
	v_pk_mul_f32 v[40:41], v[40:41], v[40:41] op_sel:[0,1] op_sel_hi:[1,0]
	v_cndmask_b32_e64 v39, 1.0, v48, s[42:43]
	v_mov_b32_e32 v61, v40
	v_mul_f32_e32 v45, v39, v40
	v_pk_mul_f32 v[40:41], v[58:59], v[60:61]
	v_cndmask_b32_e64 v37, 1.0, v57, s[42:43]
	v_pk_mul_f32 v[42:43], v[42:43], v[40:41]
	v_mul_f32_e32 v48, v37, v41
	v_mov_b32_e32 v39, v42
	v_mov_b32_e32 v40, v42
	s_nop 1
	v_permlane32_swap_b32_e32 v39, v40
	v_xor_b32_e32 v39, v39, v40
	v_xor_b32_e32 v39, v39, v42
	v_cndmask_b32_e64 v37, 1.0, v39, s[42:43]
	v_mul_f32_e32 v64, v37, v43
	v_mul_f32_e32 v37, v42, v39
	v_xor_b32_e32 v35, v35, v51
	v_mul_f32_e32 v37, v37, v43
	v_mul_f32_e32 v53, v46, v47
	v_pk_mul_f32 v[40:41], v[52:53], v[36:37]
	v_pk_mul_f32 v[42:43], v[50:51], v[34:35]
	v_cndmask_b32_e64 v39, 1.0, v47, s[42:43]
	v_pk_mul_f32 v[42:43], v[42:43], v[40:41]
	v_mul_f32_e32 v57, v39, v37
	v_cndmask_b32_e64 v39, 1.0, v35, s[42:43]
	v_mov_b32_e32 v35, v42
	v_mov_b32_e32 v37, v42
	s_nop 1
	v_permlane32_swap_b32_e32 v35, v37
	v_xor_b32_e32 v35, v35, v37
	v_xor_b32_e32 v35, v35, v42
	v_mul_f32_e32 v39, v39, v41
	v_cndmask_b32_e64 v37, 1.0, v35, s[42:43]
	v_mul_f32_e32 v37, v37, v43
	v_mul_f32_e32 v35, v42, v35
	v_mul_f32_e32 v50, v121, v39
	v_mul_f32_e32 v39, v120, v39
	v_mul_f32_e32 v91, v35, v43
	v_mul_f32_e32 v35, v36, v37
	v_mul_f32_e32 v51, v117, v39
	v_mul_f32_e32 v39, v116, v39
	v_mul_f32_e32 v42, v105, v35
	v_mul_f32_e32 v35, v52, v35
	v_mul_f32_e32 v52, v113, v39
	v_mul_f32_e32 v39, v55, v39
	v_mul_f32_e32 v43, v122, v45
	v_mul_f32_e32 v55, v54, v39
	v_mul_f32_e32 v39, v123, v45
	v_mul_f32_e32 v45, v118, v43
	v_mul_f32_e32 v41, v119, v43
	v_mul_f32_e32 v43, v115, v45
	v_mul_f32_e32 v45, v114, v45
	v_mul_f32_e32 v46, v112, v45
	v_mul_f32_e32 v45, v133, v57
	v_mul_f32_e32 v54, v134, v57
	v_mul_f32_e32 v57, v130, v45
	v_mul_f32_e32 v45, v129, v45
	v_mul_f32_e32 v59, v127, v45
	v_mul_f32_e32 v45, v126, v45
	v_mul_f32_e32 v34, v34, v35
	v_mul_f32_e32 v36, v110, v48
	v_mul_f32_e32 v61, v124, v45
	v_mul_f32_e32 v45, v136, v49
	v_mul_f32_e32 v49, v135, v49
	v_add_u32_e32 v90, s13, v87
	v_mul_f32_e32 v40, v109, v37
	v_mul_f32_e32 v44, v102, v35
	v_mul_f32_e32 v47, v98, v34
	v_mul_f32_e32 v34, v111, v48
	v_mul_f32_e32 v35, v108, v36
	v_mul_f32_e32 v53, v131, v49
	ds_read_b64_tr_b16 v[108:109], v90 offset:8192
	ds_read_b64_tr_b16 v[110:111], v90 offset:8704
	ds_read_b64_tr_b16 v[112:113], v90 offset:12288
	ds_read_b64_tr_b16 v[114:115], v90 offset:12800
	v_mul_f32_e32 v48, v132, v49
	v_mul_f32_e32 v49, v128, v53
	v_mul_f32_e32 v38, v38, v53
	v_mul_f32_e32 v53, v60, v64
	v_mul_f32_e32 v37, v107, v36
	v_mul_f32_e32 v63, v63, v53
	v_mul_f32_e32 v53, v58, v53
	v_mul_f32_e32 v36, v104, v37
	v_mul_f32_e32 v37, v103, v37
	v_mul_f32_e32 v62, v62, v64
	v_mul_f32_e32 v64, v139, v53
	v_mul_f32_e32 v53, v56, v53
	v_mul_f32_e32 v37, v100, v37
	v_mul_f32_e32 v65, v137, v53
	v_mul_f32_e32 v53, v145, v101
	v_mul_f32_e32 v58, v144, v101
	v_cvt_pk_bf16_f32 v100, v47, v44
	v_cvt_pk_bf16_f32 v101, v42, v40
	v_cvt_pk_bf16_f32 v102, v55, v52
	v_cvt_pk_bf16_f32 v103, v51, v50
	v_mul_f32_e32 v38, v125, v38
	v_mul_f32_e32 v60, v142, v58
	s_waitcnt lgkmcnt(2)
; #define LAS __attribute__((address_space(3)))
; #define MFMA32(a, b, c) __builtin_amdgcn_mfma_f32_32x32x16_bf16((a), (b), (c), 0, 0, 0)
; DI s16x4 vtr(LAS const unsigned char* p) { return __builtin_bit_cast(s16x4, __builtin_amdgcn_ds_read_tr16_b64_v4i16((LAS v4i16_t*)p)); }
; DI void pv_tile(f32x16& o0, f32x16& o1, LAS const unsigned char* Vs, const f32x16& p0, const f32x16& p1, int lane) {
;     const int h = lane >> 5;
;     LAS const unsigned char* vb = Vs + (4 * h + ((lane & 15) >> 2)) * 64 + ((lane >> 4) & 1) * 32 + (lane & 3) * 8;
; #pragma unroll
;     for (int kh = 0; kh < 2; ++kh)
; #pragma unroll
;         for (int s2 = 0; s2 < 2; ++s2) {
;             const bf16x8 pb = kh ? pack8(p1, s2) : pack8(p0, s2);
;             const int ro = (32 * kh + 16 * s2) * 64;
;             const s16x4 l0 = vtr(vb + ro), h0 = vtr(vb + ro + 512), l1 = vtr(vb + 4096 + ro), h1 = vtr(vb + 4096 + ro + 512);
;             const bf16x8 v0 = (bf16x8){l0[0], l0[1], l0[2], l0[3], h0[0], h0[1], h0[2], h0[3]};
;             const bf16x8 v1 = (bf16x8){l1[0], l1[1], l1[2], l1[3], h1[0], h1[1], h1[2], h1[3]};
;             o0 = MFMA32(v0, pb, o0); o1 = MFMA32(v1, pb, o1);
;         }
; DI void sb_wg_unit(bf16_t* act, int b, int hh, int Qb, LAS unsigned char* lds, volatile LAS unsigned* ctl, int tid, int wid, int lane) {
;     ...
;             C = run;
;             pv_tile(o0, o1, Vs, p0, p1, lane);
;             if (__all(C < 1.17549435e-38f)) done = true;
;             --t;
	v_mfma_f32_32x32x16_bf16 v[18:33], v[108:111], v[100:103], v[18:33]
	v_mul_f32_e32 v56, v143, v58
	v_mul_f32_e32 v58, v141, v60
	v_mul_f32_e32 v60, v140, v60
	v_mul_f32_e32 v60, v138, v60
	v_cmp_gt_f32_e32 vcc, s8, v91
	s_cmp_eq_u64 vcc, exec
	s_cselect_b64 s[8:9], -1, 0
	s_waitcnt lgkmcnt(0)
	v_mfma_f32_32x32x16_bf16 v[2:17], v[112:115], v[100:103], v[2:17]
	v_cvt_pk_bf16_f32 v102, v65, v64
	v_cvt_pk_bf16_f32 v103, v63, v62
	ds_read_b64_tr_b16 v[62:63], v90 offset:9216
	ds_read_b64_tr_b16 v[64:65], v90 offset:9728
	ds_read_b64_tr_b16 v[108:109], v90 offset:13312
	ds_read_b64_tr_b16 v[110:111], v90 offset:13824
	v_cvt_pk_bf16_f32 v100, v61, v59
	v_cvt_pk_bf16_f32 v101, v57, v54
	s_add_i32 s24, s24, -1
	s_cmp_le_i32 s10, s23
	s_waitcnt lgkmcnt(2)
	v_mfma_f32_32x32x16_bf16 v[18:33], v[62:65], v[100:103], v[18:33]
	v_cvt_pk_bf16_f32 v62, v37, v36
	v_cvt_pk_bf16_f32 v63, v35, v34
	v_cvt_pk_bf16_f32 v64, v46, v43
	v_cvt_pk_bf16_f32 v65, v41, v39
	ds_read_b64_tr_b16 v[34:35], v90 offset:10240
	ds_read_b64_tr_b16 v[36:37], v90 offset:10752
	ds_read_b64_tr_b16 v[40:41], v90 offset:14336
	ds_read_b64_tr_b16 v[42:43], v90 offset:14848
	s_cselect_b64 s[10:11], -1, 0
	s_or_b64 s[10:11], s[8:9], s[10:11]
	s_waitcnt lgkmcnt(4)
	v_mfma_f32_32x32x16_bf16 v[2:17], v[108:111], v[100:103], v[2:17]
	s_sub_i32 s12, s12, 64
	v_add_u32_e32 v87, 0x4000, v87
	s_andn2_b64 vcc, exec, s[10:11]
	s_waitcnt lgkmcnt(2)
	v_mfma_f32_32x32x16_bf16 v[18:33], v[34:37], v[62:65], v[18:33]
	v_cvt_pk_bf16_f32 v34, v38, v49
	v_cvt_pk_bf16_f32 v35, v48, v45
	v_cvt_pk_bf16_f32 v36, v60, v58
	v_cvt_pk_bf16_f32 v37, v56, v53
	s_waitcnt lgkmcnt(0)
	v_mfma_f32_32x32x16_bf16 v[2:17], v[40:43], v[62:65], v[2:17]
	ds_read_b64_tr_b16 v[38:39], v90 offset:11264
	ds_read_b64_tr_b16 v[40:41], v90 offset:11776
	ds_read_b64_tr_b16 v[42:43], v90 offset:15360
	ds_read_b64_tr_b16 v[44:45], v90 offset:15872
	s_waitcnt lgkmcnt(2)
	v_mfma_f32_32x32x16_bf16 v[18:33], v[38:41], v[34:37], v[18:33]
	s_waitcnt lgkmcnt(0)
	v_mfma_f32_32x32x16_bf16 v[2:17], v[42:45], v[34:37], v[2:17]
	s_cbranch_vccnz .LBB0_355
